# attnA: mid-tile barrier after QK + next tile K fragments prefetched into buffers freed at end of PV
# baseline (speedup 1.0000x reference)
.LBB0_484:
	s_lshl_b32 s3, s5, 7
	s_and_b32 s23, s3, 0x380
	v_ashrrev_i32_e32 v207, 31, v206
	s_ashr_i32 s5, s4, 31
	s_add_i32 s24, s23, s11
	v_lshlrev_b64 v[4:5], 12, v[206:207]
	s_lshl_b64 s[4:5], s[4:5], 10
	v_lshl_add_u64 v[4:5], s[80:81], 0, v[4:5]
	s_ashr_i32 s25, s24, 31
	s_or_b32 s3, s4, s23
	v_lshl_add_u64 v[4:5], s[24:25], 1, v[4:5]
	v_lshlrev_b32_e32 v184, 1, v192
	s_mul_i32 s24, s3, 0x2200
	s_mul_hi_u32 s3, s3, 0x2200
	s_mul_i32 s4, s5, 0x2200
	s_or_b32 s17, s10, 4
	v_lshl_add_u64 v[4:5], v[4:5], 0, v[184:185]
	s_add_i32 s3, s3, s4
	s_lshl_b32 s4, s23, 1
	global_load_dwordx4 v[160:163], v[4:5], off
	global_load_dwordx4 v[156:159], v[4:5], off offset:32
	global_load_dwordx4 v[152:155], v[4:5], off offset:64
	global_load_dwordx4 v[148:151], v[4:5], off offset:96
	s_add_u32 s4, s28, s4
	v_add_u32_e32 v4, v2, v217
	s_addc_u32 s5, s29, 0
	v_readlane_b32 s36, v241, 45
	v_ashrrev_i32_e32 v5, 31, v4
	v_add_u32_e32 v2, v2, v218
	v_readlane_b32 s37, v241, 46
	s_add_u32 s24, s36, s24
	v_lshlrev_b64 v[4:5], 12, v[4:5]
	v_ashrrev_i32_e32 v3, 31, v2
	s_addc_u32 s25, s37, s3
	v_lshl_add_u64 v[4:5], s[4:5], 0, v[4:5]
	v_lshlrev_b64 v[2:3], 12, v[2:3]
	s_lshl_b32 s3, s26, 1
	v_lshl_add_u64 v[4:5], v[4:5], 0, v[200:201]
	v_lshl_add_u64 v[2:3], s[4:5], 0, v[2:3]
	s_add_u32 s26, s24, s3
	global_load_dwordx4 v[4:7], v[4:5], off
	v_lshl_add_u64 v[2:3], v[2:3], 0, v[202:203]
	s_addc_u32 s27, s25, 0
	v_mov_b32_e32 v205, v185
	global_load_dwordx4 v[8:11], v[2:3], off
	v_lshl_add_u64 v[2:3], s[26:27], 0, v[204:205]
	v_lshl_add_u64 v[12:13], v[2:3], 0, v[196:197]
	global_load_dwordx4 v[12:15], v[12:13], off
	v_lshl_add_u64 v[2:3], v[2:3], 0, v[198:199]
	global_load_dwordx4 v[16:19], v[2:3], off
	s_or_b32 s3, s16, 64
	s_add_i32 s34, s31, 0x4040
	s_and_b64 s[26:27], s[6:7], exec
	s_cselect_b32 s3, s3, s34
	v_add_u32_e32 v2, s3, v217
	v_ashrrev_i32_e32 v3, 31, v2
	v_add_u32_e32 v20, v193, v231
	v_lshlrev_b64 v[2:3], 12, v[2:3]
	v_add_u32_e32 v237, 0x8800, v20
	v_lshl_add_u64 v[2:3], s[4:5], 0, v[2:3]
	v_lshl_add_u64 v[2:3], v[2:3], 0, v[200:201]
	v_add_u32_e32 v21, v193, v232
	v_add_u32_e32 v236, 0x8800, v21
	v_lshl_add_u64 v[208:209], s[24:25], 0, v[204:205]
	v_readlane_b32 s36, v242, 63
	v_readlane_b32 s37, v241, 0
	v_readlane_b32 s38, v241, 1
	v_readlane_b32 s39, v241, 2
	v_readlane_b32 s40, v241, 3
	v_readlane_b32 s41, v241, 4
	v_readlane_b32 s42, v241, 5
	v_readlane_b32 s43, v241, 6
	v_readlane_b32 s44, v241, 7
	v_readlane_b32 s45, v241, 8
	v_readlane_b32 s46, v241, 9
	v_readlane_b32 s47, v241, 10
	v_readlane_b32 s48, v241, 11
	v_readlane_b32 s49, v241, 12
	v_readlane_b32 s50, v241, 13
	v_readlane_b32 s51, v241, 14
	v_mov_b64_e32 v[34:35], s[36:37]
	v_mov_b64_e32 v[36:37], s[38:39]
	v_mov_b64_e32 v[38:39], s[40:41]
	v_mov_b64_e32 v[40:41], s[42:43]
	v_mov_b64_e32 v[42:43], s[44:45]
	v_mov_b64_e32 v[44:45], s[46:47]
	v_mov_b64_e32 v[46:47], s[48:49]
	v_mov_b64_e32 v[48:49], s[50:51]
	v_mov_b64_e32 v[100:101], s[70:71]
	v_mov_b64_e32 v[98:99], s[68:69]
	v_lshl_add_u64 v[210:211], s[4:5], 0, v[200:201]
	v_lshl_add_u64 v[212:213], s[4:5], 0, v[202:203]
	v_readlane_b32 s48, v241, 29
	s_waitcnt vmcnt(3)
	ds_write_b128 v234, v[4:7]
	s_waitcnt vmcnt(2)
	ds_write_b128 v235, v[8:11]
	v_add_u32_e32 v6, s3, v218
	s_lshl_b32 s3, s22, 1
	v_ashrrev_i32_e32 v7, 31, v6
	s_add_u32 s26, s24, s3
	v_lshlrev_b64 v[6:7], 12, v[6:7]
	s_addc_u32 s27, s25, 0
	s_waitcnt vmcnt(1)
	ds_write2_b64 v237, v[12:13], v[14:15] offset1:2
	v_lshl_add_u64 v[6:7], s[4:5], 0, v[6:7]
	v_lshl_add_u64 v[14:15], s[26:27], 0, v[204:205]
	global_load_dwordx4 v[2:5], v[2:3], off
	v_lshl_add_u64 v[6:7], v[6:7], 0, v[202:203]
	v_lshl_add_u64 v[10:11], v[14:15], 0, v[196:197]
	global_load_dwordx4 v[6:9], v[6:7], off
	v_lshl_add_u64 v[14:15], v[14:15], 0, v[198:199]
	global_load_dwordx4 v[10:13], v[10:11], off
	s_waitcnt vmcnt(3)
	ds_write2_b64 v236, v[16:17], v[18:19] offset1:2
	global_load_dwordx4 v[14:17], v[14:15], off
	s_add_i32 s22, s31, 0x3000
	s_sub_i32 s3, 0x42, s10
	s_and_b64 s[6:7], s[6:7], exec
	s_cselect_b32 s3, 2, s3
	s_lshl_b32 s7, s3, 6
	s_or_b32 s6, s16, 0x80
	s_add_i32 s24, s22, s7
	s_waitcnt lgkmcnt(0)
	s_barrier
	s_cmp_lt_u32 s3, 64
	s_cselect_b32 s6, s6, s24
	s_cselect_b32 s3, 0x80, s7
	s_lshl_b32 s78, s3, 1
	s_waitcnt vmcnt(3)
	ds_write_b128 v234, v[2:5] offset:17408
	s_waitcnt vmcnt(2)
	ds_write_b128 v235, v[6:9] offset:17408
	v_add_u32_e32 v2, 0xd000, v20
	s_waitcnt vmcnt(1)
	ds_write2_b64 v2, v[10:11], v[12:13] offset1:2
	v_add_u32_e32 v2, 0xd000, v21
	s_waitcnt vmcnt(0)
	ds_write2_b64 v2, v[14:15], v[16:17] offset1:2
	v_add_u32_e32 v2, s6, v217
	v_ashrrev_i32_e32 v3, 31, v2
	v_lshlrev_b64 v[2:3], 12, v[2:3]
	v_lshl_add_u64 v[2:3], s[4:5], 0, v[2:3]
	v_lshl_add_u64 v[2:3], v[2:3], 0, v[200:201]
	global_load_dwordx4 v[164:167], v[2:3], off
	v_add_u32_e32 v2, s6, v218
	v_ashrrev_i32_e32 v3, 31, v2
	v_lshlrev_b64 v[2:3], 12, v[2:3]
	v_lshl_add_u64 v[2:3], s[4:5], 0, v[2:3]
	v_lshl_add_u64 v[2:3], v[2:3], 0, v[202:203]
	global_load_dwordx4 v[168:171], v[2:3], off
	v_lshl_add_u64 v[2:3], v[208:209], 0, s[78:79]
	v_lshl_add_u64 v[4:5], v[2:3], 0, v[196:197]
	v_lshl_add_u64 v[2:3], v[2:3], 0, v[198:199]
	global_load_dwordx4 v[176:179], v[4:5], off
	global_load_dwordx4 v[172:175], v[2:3], off
	ds_read_b128 v[50:53], v214 offset:8704
	ds_read_b128 v[18:21], v214
	ds_read_b128 v[54:57], v214 offset:32
	s_waitcnt lgkmcnt(1)
	v_mfma_f32_32x32x16_bf16 v[2:17], v[18:21], v[160:163], v[34:49]
	s_mov_b32 s5, 0
	s_sub_i32 s6, 0, s10
	v_mfma_f32_32x32x16_bf16 v[18:33], v[50:53], v[160:163], v[34:49]
	s_nop 6
	ds_read_b128 v[34:37], v214 offset:8736
	s_waitcnt lgkmcnt(1)
	v_mfma_f32_32x32x16_bf16 v[2:17], v[54:57], v[156:159], v[2:17]
	s_waitcnt lgkmcnt(0)
	v_mfma_f32_32x32x16_bf16 v[18:33], v[34:37], v[156:159], v[18:33]
	ds_read_b128 v[34:37], v214 offset:64
	ds_read_b128 v[38:41], v214 offset:8768
	s_waitcnt lgkmcnt(1)
	v_mfma_f32_32x32x16_bf16 v[2:17], v[34:37], v[152:155], v[2:17]
	s_waitcnt lgkmcnt(0)
	v_mfma_f32_32x32x16_bf16 v[18:33], v[38:41], v[152:155], v[18:33]
	ds_read_b128 v[34:37], v214 offset:96
	ds_read_b128 v[38:41], v214 offset:8800
	s_waitcnt lgkmcnt(1)
	v_mfma_f32_32x32x16_bf16 v[2:17], v[34:37], v[148:151], v[2:17]
	s_waitcnt lgkmcnt(0)
	v_mfma_f32_32x32x16_bf16 v[18:33], v[38:41], v[148:151], v[18:33]
	s_nop 9
	v_max_f32_e32 v34, v3, v3
	v_max_f32_e32 v35, v2, v2
	v_max_f32_e32 v34, v35, v34
	v_max3_f32 v35, v5, v6, v7
	v_max3_f32 v34, v34, v4, v8
	v_max3_f32 v35, v35, v10, v11
	v_max3_f32 v34, v34, v9, v12
	v_max3_f32 v36, v18, v19, v20
	v_max3_f32 v37, v21, v22, v23
	v_max3_f32 v36, v36, v24, v25
	v_max3_f32 v37, v37, v26, v27
	v_max3_f32 v35, v35, v14, v15
	v_max3_f32 v36, v36, v28, v29
	v_max3_f32 v34, v34, v13, v16
	v_max3_f32 v37, v37, v30, v31
	v_max3_f32 v36, v36, v32, v33
	v_max3_f32 v34, v34, v17, v35
	v_max3_f32 v34, v34, v36, v37
	ds_bpermute_b32 v35, v67, v34
	s_waitcnt lgkmcnt(0)
	v_max_f32_e32 v35, v35, v35
	v_max_f32_e32 v205, v34, v35
	v_sub_f32_e32 v2, v2, v205
	v_sub_f32_e32 v3, v3, v205
	v_sub_f32_e32 v4, v4, v205
	v_sub_f32_e32 v5, v5, v205
	v_exp_f32_e32 v2, v2
	v_exp_f32_e32 v3, v3
	v_exp_f32_e32 v4, v4
	v_exp_f32_e32 v5, v5
	v_sub_f32_e32 v6, v6, v205
	v_sub_f32_e32 v7, v7, v205
	v_sub_f32_e32 v8, v8, v205
	v_sub_f32_e32 v9, v9, v205
	v_exp_f32_e32 v6, v6
	v_exp_f32_e32 v7, v7
	v_exp_f32_e32 v8, v8
	v_exp_f32_e32 v9, v9
	v_cvt_pk_bf16_f32 v68, v2, v3
	v_cvt_pk_bf16_f32 v69, v4, v5
	ds_read_b128 v[2:5], v215 offset:34816
	ds_read_b128 v[72:75], v215 offset:34848
	v_cvt_pk_bf16_f32 v70, v6, v7
	v_cvt_pk_bf16_f32 v71, v8, v9
	v_sub_f32_e32 v10, v10, v205
	v_sub_f32_e32 v11, v11, v205
	s_waitcnt lgkmcnt(1)
	v_mfma_f32_32x32x16_bf16 v[50:65], v[2:5], v[68:71], 0
	ds_read_b128 v[2:5], v215 offset:39424
	v_sub_f32_e32 v12, v12, v205
	v_sub_f32_e32 v13, v13, v205
	v_sub_f32_e32 v14, v14, v205
	v_sub_f32_e32 v15, v15, v205
	v_sub_f32_e32 v16, v16, v205
	v_sub_f32_e32 v17, v17, v205
	v_exp_f32_e32 v10, v10
	v_exp_f32_e32 v11, v11
	v_exp_f32_e32 v12, v12
	v_exp_f32_e32 v13, v13
	v_exp_f32_e32 v14, v14
	v_exp_f32_e32 v15, v15
	v_exp_f32_e32 v16, v16
	v_exp_f32_e32 v17, v17
	v_cvt_pk_bf16_f32 v94, v10, v11
	v_cvt_pk_bf16_f32 v95, v12, v13
	v_cvt_pk_bf16_f32 v96, v14, v15
	v_cvt_pk_bf16_f32 v97, v16, v17
	v_sub_f32_e32 v18, v18, v205
	v_sub_f32_e32 v19, v19, v205
	s_waitcnt lgkmcnt(1)
	v_mfma_f32_32x32x16_bf16 v[50:65], v[72:75], v[94:97], v[50:65]
	ds_read_b128 v[72:75], v215 offset:39456
	v_sub_f32_e32 v20, v20, v205
	v_sub_f32_e32 v21, v21, v205
	v_sub_f32_e32 v22, v22, v205
	v_sub_f32_e32 v23, v23, v205
	v_sub_f32_e32 v24, v24, v205
	v_sub_f32_e32 v25, v25, v205
	s_waitcnt lgkmcnt(1)
	v_mfma_f32_32x32x16_bf16 v[34:49], v[2:5], v[68:71], 0
	ds_read_b128 v[2:5], v215 offset:44032
	v_sub_f32_e32 v26, v26, v205
	v_sub_f32_e32 v27, v27, v205
	v_sub_f32_e32 v28, v28, v205
	v_sub_f32_e32 v29, v29, v205
	v_sub_f32_e32 v30, v30, v205
	v_sub_f32_e32 v31, v31, v205
	v_sub_f32_e32 v32, v32, v205
	v_sub_f32_e32 v33, v33, v205
	v_exp_f32_e32 v18, v18
	v_exp_f32_e32 v19, v19
	v_exp_f32_e32 v20, v20
	v_exp_f32_e32 v21, v21
	v_exp_f32_e32 v22, v22
	v_exp_f32_e32 v23, v23
	v_exp_f32_e32 v24, v24
	v_exp_f32_e32 v25, v25
	v_exp_f32_e32 v26, v26
	v_exp_f32_e32 v27, v27
	v_exp_f32_e32 v28, v28
	v_exp_f32_e32 v29, v29
	v_exp_f32_e32 v30, v30
	v_exp_f32_e32 v31, v31
	v_exp_f32_e32 v32, v32
	v_exp_f32_e32 v33, v33
	s_waitcnt lgkmcnt(1)
	v_mfma_f32_32x32x16_bf16 v[34:49], v[72:75], v[94:97], v[34:49]
	ds_read_b128 v[72:75], v215 offset:44064
	v_cvt_pk_bf16_f32 v90, v18, v19
	v_cvt_pk_bf16_f32 v91, v20, v21
	v_cvt_pk_bf16_f32 v92, v22, v23
	v_cvt_pk_bf16_f32 v93, v24, v25
	v_cvt_pk_bf16_f32 v86, v26, v27
	v_cvt_pk_bf16_f32 v87, v28, v29
	v_cvt_pk_bf16_f32 v88, v30, v31
	v_cvt_pk_bf16_f32 v89, v32, v33
	s_waitcnt lgkmcnt(1)
	v_mfma_f32_32x32x16_bf16 v[18:33], v[2:5], v[68:71], 0
	ds_read_b128 v[2:5], v215 offset:48640
	v_xor_b32_e32 v84, 0x80000000, v205
	v_mov_b32_e32 v85, v84
	s_waitcnt lgkmcnt(1)
	v_mfma_f32_32x32x16_bf16 v[18:33], v[72:75], v[94:97], v[18:33]
	ds_read_b128 v[72:75], v215 offset:48672
	s_waitcnt lgkmcnt(1)
	v_mfma_f32_32x32x16_bf16 v[2:17], v[2:5], v[68:71], 0
	s_waitcnt lgkmcnt(0)
	v_mfma_f32_32x32x16_bf16 v[2:17], v[72:75], v[94:97], v[2:17]
	ds_read_b128 v[72:75], v215 offset:34880
	s_waitcnt lgkmcnt(0)
	v_mfma_f32_32x32x16_bf16 v[50:65], v[72:75], v[90:93], v[50:65]
	ds_read_b128 v[72:75], v215 offset:39488
	s_waitcnt lgkmcnt(0)
	v_mfma_f32_32x32x16_bf16 v[34:49], v[72:75], v[90:93], v[34:49]
	ds_read_b128 v[72:75], v215 offset:44096
	s_waitcnt lgkmcnt(0)
	v_mfma_f32_32x32x16_bf16 v[18:33], v[72:75], v[90:93], v[18:33]
	ds_read_b128 v[72:75], v215 offset:48704
	s_waitcnt lgkmcnt(0)
	v_mfma_f32_32x32x16_bf16 v[2:17], v[72:75], v[90:93], v[2:17]
	ds_read_b128 v[72:75], v215 offset:34912
	s_waitcnt lgkmcnt(0)
	v_mfma_f32_32x32x16_bf16 v[50:65], v[72:75], v[86:89], v[50:65]
	ds_read_b128 v[72:75], v215 offset:39520
	s_waitcnt lgkmcnt(0)
	v_mfma_f32_32x32x16_bf16 v[34:49], v[72:75], v[86:89], v[34:49]
	ds_read_b128 v[72:75], v215 offset:44128
	s_waitcnt lgkmcnt(0)
	v_mfma_f32_32x32x16_bf16 v[18:33], v[72:75], v[86:89], v[18:33]
	ds_read_b128 v[72:75], v215 offset:48736
	s_waitcnt lgkmcnt(0)
	s_barrier
	v_mfma_f32_32x32x16_bf16 v[2:17], v[72:75], v[86:89], v[2:17]
	v_mfma_f32_32x32x16_bf16 v[68:83], v[98:101], v[68:71], 0
	v_mfma_f32_32x32x16_bf16 v[68:83], v[98:101], v[94:97], v[68:83]
	v_mov_b32_e32 v94, v84
	v_mov_b32_e32 v95, v84
	v_mov_b32_e32 v96, v84
	v_mov_b32_e32 v97, v84
	v_mfma_f32_32x32x16_bf16 v[68:83], v[98:101], v[90:93], v[68:83]
	v_mov_b32_e32 v90, v84
	v_mov_b32_e32 v91, v84
	v_mov_b32_e32 v92, v84
	v_mov_b32_e32 v93, v84
	v_mfma_f32_32x32x16_bf16 v[68:83], v[98:101], v[86:89], v[68:83]
	v_mov_b32_e32 v86, v84
	v_mov_b32_e32 v87, v84
	v_mov_b32_e32 v88, v84
	v_mov_b32_e32 v89, v84
	v_mov_b32_e32 v98, v84
	v_mov_b32_e32 v99, v84
	s_add_i32 s3, s5, 1
	s_and_b32 s3, s3, 1
	s_mul_i32 s3, s3, 0x4400
	v_add_u32_e32 v238, s3, v214
	ds_read_b128 v[100:103], v238
	ds_read_b128 v[104:107], v238 offset:8704
	ds_read_b128 v[108:111], v238 offset:32
	ds_read_b128 v[112:115], v238 offset:8736
	ds_read_b128 v[244:247], v238 offset:64
	ds_read_b128 v[248:251], v238 offset:8768
.LBB0_485:
	s_add_i32 s5, s5, 1
	s_and_b32 s24, s5, 1
	s_mul_i32 s3, s24, 0x4400
	s_mulk_i32 s24, 0x4800
	v_add_u32_e32 v238, s3, v214
	v_add_u32_e32 v239, s24, v215
	s_add_i32 s3, s5, 1
	s_and_b32 s4, s3, 1
	s_mul_i32 s7, s4, 0x4400
	s_mulk_i32 s4, 0x4800
	v_add3_u32 v240, s7, v219, v228
	v_add3_u32 v243, s7, v229, v230
	s_waitcnt vmcnt(0)
	ds_write_b128 v240, v[164:167]
	ds_write_b128 v243, v[168:171]
	v_add_u32_e32 v240, s4, v193
	v_add_u32_e32 v243, v240, v231
	v_add_u32_e32 v240, v240, v232
	v_add_u32_e32 v243, 0x8800, v243
	v_add_u32_e32 v240, 0x8800, v240
	ds_write2_b64 v243, v[176:177], v[178:179] offset1:2
	ds_write2_b64 v240, v[172:173], v[174:175] offset1:2
	s_waitcnt lgkmcnt(9)
	v_mfma_f32_32x32x16_bf16 v[116:131], v[100:103], v[160:163], v[84:99]
	ds_read_b128 v[100:103], v238 offset:96
	s_add_i32 s24, s5, 2
	s_add_i32 s3, s6, s5
	s_addk_i32 s3, 0x42
	s_cmp_lt_u32 s24, s10
	s_waitcnt lgkmcnt(9)
	v_mfma_f32_32x32x16_bf16 v[132:147], v[104:107], v[160:163], v[84:99]
	ds_read_b128 v[104:107], v238 offset:8800
	s_cselect_b32 s3, s24, s3
	s_lshl_b32 s78, s3, 6
	s_add_i32 s24, s78, s22
	s_or_b32 s25, s78, s16
	s_waitcnt lgkmcnt(9)
	v_mfma_f32_32x32x16_bf16 v[116:131], v[108:111], v[156:159], v[116:131]
	ds_read_b128 v[108:111], v239 offset:34816
	s_cmp_lt_u32 s3, 64
	s_cselect_b32 s3, s25, s24
	v_add_u32_e32 v252, s3, v217
	v_add_u32_e32 v254, s3, v218
	s_waitcnt lgkmcnt(9)
	v_mfma_f32_32x32x16_bf16 v[132:147], v[112:115], v[156:159], v[132:147]
	ds_read_b128 v[112:115], v239 offset:39424
	v_ashrrev_i32_e32 v253, 31, v252
	v_ashrrev_i32_e32 v255, 31, v254
	v_lshlrev_b64 v[252:253], 12, v[252:253]
	v_lshlrev_b64 v[254:255], 12, v[254:255]
	s_waitcnt lgkmcnt(9)
	v_mfma_f32_32x32x16_bf16 v[116:131], v[244:247], v[152:155], v[116:131]
	ds_read_b128 v[244:247], v239 offset:44032
	v_lshl_add_u64 v[252:253], v[210:211], 0, v[252:253]
	v_lshl_add_u64 v[254:255], v[212:213], 0, v[254:255]
	global_load_dwordx4 v[164:167], v[252:253], off
	global_load_dwordx4 v[168:171], v[254:255], off
	s_waitcnt lgkmcnt(9)
	v_mfma_f32_32x32x16_bf16 v[132:147], v[248:251], v[152:155], v[132:147]
	ds_read_b128 v[248:251], v239 offset:48640
	v_lshl_add_u64 v[252:253], s[78:79], 1, v[208:209]
	v_lshl_add_u64 v[254:255], v[252:253], 0, v[196:197]
	v_lshl_add_u64 v[252:253], v[252:253], 0, v[198:199]
	global_load_dwordx4 v[176:179], v[254:255], off
	s_waitcnt lgkmcnt(5)
	v_mfma_f32_32x32x16_bf16 v[116:131], v[100:103], v[148:151], v[116:131]
	ds_read_b128 v[100:103], v239 offset:34848
	global_load_dwordx4 v[172:175], v[252:253], off
	s_waitcnt lgkmcnt(5)
	v_mfma_f32_32x32x16_bf16 v[132:147], v[104:107], v[148:151], v[132:147]
	ds_read_b128 v[104:107], v239 offset:39456
	s_barrier
	v_add_u32_e32 v240, s7, v214
	s_nop 6
	v_max3_f32 v252, v116, v117, v118
	v_max3_f32 v253, v119, v120, v121
	v_max3_f32 v252, v252, v122, v123
	v_max3_f32 v253, v253, v124, v125
	v_max3_f32 v252, v252, v126, v127
	v_max3_f32 v253, v253, v128, v129
	v_max3_f32 v252, v252, v130, v131
	v_max3_f32 v254, v132, v133, v134
	v_max3_f32 v255, v135, v136, v137
	v_max3_f32 v254, v254, v138, v139
	v_max3_f32 v255, v255, v140, v141
	v_max3_f32 v254, v254, v142, v143
	v_max3_f32 v255, v255, v144, v145
	v_max3_f32 v254, v254, v146, v147
	v_max3_f32 v252, v252, v253, v254
	v_max_f32_e32 v252, v252, v255
	v_mov_b32_e32 v253, v252
	s_nop 1
	v_permlane32_swap_b32_e32 v252, v253
	v_max_f32_e32 v252, v252, v253
	v_cmp_lt_f32_e32 vcc, s52, v252
	s_cbranch_vccnz .Lattn_a_rescale
.Lattn_a_exp:
	v_exp_f32_e32 v116, v116
	v_exp_f32_e32 v117, v117
	v_exp_f32_e32 v118, v118
	v_exp_f32_e32 v119, v119
	v_exp_f32_e32 v120, v120
	v_exp_f32_e32 v121, v121
	v_exp_f32_e32 v122, v122
	v_exp_f32_e32 v123, v123
	v_cvt_pk_bf16_f32 v116, v116, v117
	v_cvt_pk_bf16_f32 v117, v118, v119
	v_cvt_pk_bf16_f32 v118, v120, v121
	v_cvt_pk_bf16_f32 v119, v122, v123
	v_mov_b64_e32 v[252:253], s[68:69]
	v_mov_b64_e32 v[254:255], s[70:71]
	s_waitcnt lgkmcnt(5)
	v_mfma_f32_32x32x16_bf16 v[50:65], v[108:111], v[116:119], v[50:65]
	v_exp_f32_e32 v124, v124
	v_exp_f32_e32 v125, v125
	ds_read_b128 v[108:111], v239 offset:44064
	s_waitcnt lgkmcnt(5)
	v_mfma_f32_32x32x16_bf16 v[34:49], v[112:115], v[116:119], v[34:49]
	v_exp_f32_e32 v126, v126
	v_exp_f32_e32 v127, v127
	ds_read_b128 v[112:115], v239 offset:48672
	s_waitcnt lgkmcnt(5)
	v_mfma_f32_32x32x16_bf16 v[18:33], v[244:247], v[116:119], v[18:33]
	v_exp_f32_e32 v128, v128
	v_exp_f32_e32 v129, v129
	ds_read_b128 v[244:247], v239 offset:34880
	s_waitcnt lgkmcnt(5)
	v_mfma_f32_32x32x16_bf16 v[2:17], v[248:251], v[116:119], v[2:17]
	v_exp_f32_e32 v130, v130
	v_exp_f32_e32 v131, v131
	v_cvt_pk_bf16_f32 v120, v124, v125
	v_cvt_pk_bf16_f32 v121, v126, v127
	v_cvt_pk_bf16_f32 v122, v128, v129
	v_cvt_pk_bf16_f32 v123, v130, v131
	ds_read_b128 v[248:251], v239 offset:39488
	s_waitcnt lgkmcnt(5)
	v_mfma_f32_32x32x16_bf16 v[50:65], v[100:103], v[120:123], v[50:65]
	v_exp_f32_e32 v132, v132
	v_exp_f32_e32 v133, v133
	ds_read_b128 v[100:103], v239 offset:44096
	s_waitcnt lgkmcnt(5)
	v_mfma_f32_32x32x16_bf16 v[34:49], v[104:107], v[120:123], v[34:49]
	v_exp_f32_e32 v134, v134
	v_exp_f32_e32 v135, v135
	ds_read_b128 v[104:107], v239 offset:48704
	s_waitcnt lgkmcnt(5)
	v_mfma_f32_32x32x16_bf16 v[18:33], v[108:111], v[120:123], v[18:33]
	v_exp_f32_e32 v136, v136
	v_exp_f32_e32 v137, v137
	ds_read_b128 v[108:111], v239 offset:34912
	s_waitcnt lgkmcnt(5)
	v_mfma_f32_32x32x16_bf16 v[2:17], v[112:115], v[120:123], v[2:17]
	v_exp_f32_e32 v138, v138
	v_exp_f32_e32 v139, v139
	v_cvt_pk_bf16_f32 v124, v132, v133
	v_cvt_pk_bf16_f32 v125, v134, v135
	v_cvt_pk_bf16_f32 v126, v136, v137
	v_cvt_pk_bf16_f32 v127, v138, v139
	ds_read_b128 v[112:115], v239 offset:39520
	s_waitcnt lgkmcnt(5)
	v_mfma_f32_32x32x16_bf16 v[50:65], v[244:247], v[124:127], v[50:65]
	v_exp_f32_e32 v140, v140
	v_exp_f32_e32 v141, v141
	ds_read_b128 v[244:247], v239 offset:44128
	s_waitcnt lgkmcnt(5)
	v_mfma_f32_32x32x16_bf16 v[34:49], v[248:251], v[124:127], v[34:49]
	v_exp_f32_e32 v142, v142
	v_exp_f32_e32 v143, v143
	ds_read_b128 v[248:251], v239 offset:48736
	s_waitcnt lgkmcnt(5)
	v_mfma_f32_32x32x16_bf16 v[18:33], v[100:103], v[124:127], v[18:33]
	v_exp_f32_e32 v144, v144
	v_exp_f32_e32 v145, v145
	ds_read_b128 v[100:103], v240
	s_waitcnt lgkmcnt(5)
	v_mfma_f32_32x32x16_bf16 v[2:17], v[104:107], v[124:127], v[2:17]
	v_exp_f32_e32 v146, v146
	v_exp_f32_e32 v147, v147
	v_cvt_pk_bf16_f32 v128, v140, v141
	v_cvt_pk_bf16_f32 v129, v142, v143
	v_cvt_pk_bf16_f32 v130, v144, v145
	v_cvt_pk_bf16_f32 v131, v146, v147
	ds_read_b128 v[104:107], v240 offset:8704
	s_waitcnt lgkmcnt(5)
	v_mfma_f32_32x32x16_bf16 v[50:65], v[108:111], v[128:131], v[50:65]
	ds_read_b128 v[108:111], v240 offset:32
	s_waitcnt lgkmcnt(5)
	v_mfma_f32_32x32x16_bf16 v[34:49], v[112:115], v[128:131], v[34:49]
	ds_read_b128 v[112:115], v240 offset:8736
	s_waitcnt lgkmcnt(5)
	v_mfma_f32_32x32x16_bf16 v[18:33], v[244:247], v[128:131], v[18:33]
	ds_read_b128 v[244:247], v240 offset:64
	s_waitcnt lgkmcnt(5)
	s_barrier
	v_mfma_f32_32x32x16_bf16 v[2:17], v[248:251], v[128:131], v[2:17]
	ds_read_b128 v[248:251], v240 offset:8768
	v_mfma_f32_32x32x16_bf16 v[68:83], v[252:255], v[116:119], v[68:83]
	v_mfma_f32_32x32x16_bf16 v[68:83], v[252:255], v[120:123], v[68:83]
	v_mfma_f32_32x32x16_bf16 v[68:83], v[252:255], v[124:127], v[68:83]
	v_mfma_f32_32x32x16_bf16 v[68:83], v[252:255], v[128:131], v[68:83]
	s_add_i32 s3, s6, s5
	s_cmp_eq_u32 s3, 2
	s_cbranch_scc0 .LBB0_485
	s_waitcnt vmcnt(0) lgkmcnt(0)
	v_mov_b64_e32 v[100:101], v[84:85]
	v_mov_b64_e32 v[102:103], v[86:87]
	v_mov_b64_e32 v[104:105], v[88:89]
	v_mov_b64_e32 v[106:107], v[90:91]
	v_mov_b64_e32 v[108:109], v[92:93]
	v_mov_b64_e32 v[110:111], v[94:95]
	v_mov_b64_e32 v[112:113], v[96:97]
	v_mov_b64_e32 v[114:115], v[98:99]
	s_branch .LBB0_491
